# MLA post-barrier lead VALU 36 (was 28)
# baseline (speedup 1.0000x reference)
; __device__ __forceinline__ float bf2f(unsigned short h) { return __uint_as_float((unsigned)h << 16); }
; template <bool MASK> __device__ __forceinline__ void sm_tile(f32x16& p0, f32x16& p1, float& mrun, float& lrun, f32x16& o0, f32x16& o1, LAS float* wsf, int kv0, int qpos, int q32, int hi) {
;     ...
;     float rs = 0.f;
; #pragma unroll
;     for (int r = 0; r < 16; ++r) { p0[r] = ex2(p0[r] - mrun); p1[r] = ex2(p1[r] - mrun); rs += p0[r] + p1[r]; }
;     rs += xhalf(rs, hi); lrun += rs;
; __device__ __forceinline__ void attn_unit_sm(int b, int h, int qb, const bf16_t* __restrict__ Q, const bf16_t* __restrict__ K, const bf16_t* __restrict__ K2, const bf16_t* __restrict__ Vt, bf16_t* __restrict__ O, const float* __restrict__ cs, LAS unsigned char* lds, int var) {
;     ...
;     SM_LOAD(0);
;     {
;         const float* cr = cs + (rowbase + q0 + wid * 32 + q32) * 32 + 8 * hi;
;         const f32x4 c0 = *(const f32x4*)cr, c1 = *(const f32x4*)(cr + 4), s0 = *(const f32x4*)(cr + 16), s1 = *(const f32x4*)(cr + 20);
;         const float cc[8] = {c0[0], c0[1], c0[2], c0[3], c1[0], c1[1], c1[2], c1[3]}, ss[8] = {s0[0], s0[1], s0[2], s0[3], s1[0], s1[1], s1[2], s1[3]};
;         float ra[8], rb[8];
; #pragma unroll
;         for (int i = 0; i < 8; ++i) { const float t1 = bf2f((unsigned short)qr[4][i]), t2 = bf2f((unsigned short)qr[5][i]); ra[i] = t1 * cc[i] - t2 * ss[i]; rb[i] = t1 * ss[i] + t2 * cc[i]; }
;         u32x4 wa, wb; wa.x = pk2(ra[0], ra[1]); wa.y = pk2(ra[2], ra[3]); wa.z = pk2(ra[4], ra[5]); wa.w = pk2(ra[6], ra[7]); wb.x = pk2(rb[0], rb[1]); wb.y = pk2(rb[2], rb[3]); wb.z = pk2(rb[4], rb[5]); wb.w = pk2(rb[6], rb[7]);
;         qr[4] = __builtin_bit_cast(bf16x8, wa); qr[5] = __builtin_bit_cast(bf16x8, wb); }
;     SM_STORE(0); __syncthreads();
;     SmState st;
; #pragma unroll
;     for (int r = 0; r < 16; ++r) { st.o0[r] = 0.f; st.o1[r] = 0.f; }
;     st.mrun = -INFINITY; st.lrun = 0.f;
;     int it = 0;
;     for (; it < ns - 2; ++it) {
;         const int cur = it & 1;
;         if (var != 2) SM_LOAD(it + 1);
; #pragma unroll
;         for (int sub = 0; sub < 2; ++sub)
;             sm_iter<false>(var, st, qr, lds + OFF_K + cur * KBUF + (sub * 64 + q32) * KP + hi * 16, lds + OFF_V + cur * VBUF + q32 * VP + sub * 128 + hi * 8, wsf, (2 * it + sub) * 64, qpos, q32, hi);
;         if (var != 2) SM_STORE(cur ^ 1);
;         __syncthreads();
.Lm3_ok4:
	s_add_i32 s19, s19, 1
	s_and_b32 s43, s19, 1
	s_mul_i32 s20, s43, 0x6800
	v_add_u32_e32 v1, s20, v175
	v_lshl_add_u64 v[162:163], v[162:163], 0, s[94:95]
	v_lshl_add_u64 v[164:165], v[164:165], 0, s[96:97]
	v_lshl_add_u64 v[166:167], v[166:167], 0, s[38:39]
	s_cmp_eq_u32 s18, s19
	s_waitcnt lgkmcnt(0)
	s_barrier
	s_cbranch_scc1 .Lm3_drain
	ds_read_b128 v[116:119], v1 offset:0
	ds_read_b128 v[120:123], v1 offset:32
	ds_read_b128 v[124:127], v1 offset:64
	ds_read_b128 v[128:131], v1 offset:96
	ds_read_b128 v[132:135], v1 offset:128
	ds_read_b128 v[136:139], v1 offset:160
	v_lshl_add_u64 v[2:3], s[22:23], 0, v[166:167]
	v_add_co_u32_e32 v4, vcc, 0x104a0000, v2
	v_lshl_add_u64 v[10:11], s[22:23], 0, v[162:163]
	s_nop 0
	v_addc_co_u32_e32 v5, vcc, 0, v3, vcc
	v_add_co_u32_e32 v2, vcc, 0x104c0000, v2
	s_and_b32 s43, s19, 1
	s_nop 0
	v_addc_co_u32_e32 v3, vcc, 0, v3, vcc
	v_add_co_u32_e32 v14, vcc, 0x12460000, v10
	global_load_dwordx4 v[6:9], v[4:5], off
	s_nop 0
	global_load_dwordx4 v[2:5], v[2:3], off
	v_addc_co_u32_e32 v15, vcc, 0, v11, vcc
	global_load_dwordx4 v[10:13], v[14:15], off offset:256
	global_load_dwordx4 v[108:111], v[14:15], off offset:384
	v_lshl_add_u64 v[14:15], s[22:23], 0, v[164:165]
	global_load_dwordx4 v[112:115], v[14:15], off
	s_mul_i32 s20, s43, 0x6800
	v_add_u32_e32 v1, s20, v175
	s_mul_i32 s20, s43, 0x4200
	v_add_u32_e32 v15, s20, v174
	v_add_u32_e32 v14, 0xd000, v15
	v_add_u32_e32 v176, 0xf000, v15
	v_exp_f32_e32 v48, v48
	v_exp_f32_e32 v49, v49
	v_exp_f32_e32 v50, v50
	v_add_f32_e32 v15, v48, v49
	v_exp_f32_e32 v51, v51
	v_cvt_pk_bf16_f32 v214, v48, v49
	v_exp_f32_e32 v52, v52
	v_add_f32_e32 v177, v50, v51
	v_exp_f32_e32 v53, v53
	v_cvt_pk_bf16_f32 v215, v50, v51
	v_exp_f32_e32 v54, v54
	v_add_f32_e32 v15, v15, v52
	v_exp_f32_e32 v55, v55
	v_add_f32_e32 v177, v177, v53
	v_exp_f32_e32 v56, v56
	v_cvt_pk_bf16_f32 v216, v52, v53
	v_exp_f32_e32 v57, v57
	v_add_f32_e32 v15, v15, v54
	v_exp_f32_e32 v58, v58
	v_add_f32_e32 v177, v177, v55
	v_exp_f32_e32 v59, v59
	v_cvt_pk_bf16_f32 v217, v54, v55
	v_exp_f32_e32 v60, v60
	v_add_f32_e32 v15, v15, v56
	v_exp_f32_e32 v61, v61
	v_add_f32_e32 v177, v177, v57
	v_exp_f32_e32 v62, v62
	v_cvt_pk_bf16_f32 v218, v56, v57
	v_exp_f32_e32 v63, v63
	v_add_f32_e32 v15, v15, v58
	v_add_f32_e32 v177, v177, v59
	v_cvt_pk_bf16_f32 v219, v58, v59
	v_add_f32_e32 v15, v15, v60
	v_add_f32_e32 v177, v177, v61
	v_cvt_pk_bf16_f32 v220, v60, v61
	v_add_f32_e32 v15, v15, v62
	s_waitcnt lgkmcnt(5)
	v_mfma_f32_32x32x16_bf16 v[64:79], v[116:119], v[84:87], v[198:213]
	v_add_f32_e32 v177, v177, v63
	s_waitcnt lgkmcnt(4)
	v_mfma_f32_32x32x16_bf16 v[64:79], v[120:123], v[88:91], v[64:79]
	v_cvt_pk_bf16_f32 v221, v62, v63
	s_waitcnt lgkmcnt(3)
	v_mfma_f32_32x32x16_bf16 v[64:79], v[124:127], v[92:95], v[64:79]
	v_add_f32_e32 v15, v15, v177
	s_waitcnt lgkmcnt(2)
	v_mfma_f32_32x32x16_bf16 v[64:79], v[128:131], v[96:99], v[64:79]
	v_add_f32_e32 v170, v170, v15
	s_waitcnt lgkmcnt(1)
	v_mfma_f32_32x32x16_bf16 v[64:79], v[132:135], v[100:103], v[64:79]
	s_waitcnt lgkmcnt(0)
	v_mfma_f32_32x32x16_bf16 v[64:79], v[136:139], v[104:107], v[64:79]
	s_waitcnt lgkmcnt(0)
	ds_read_b128 v[116:119], v1 offset:6656
	ds_read_b128 v[120:123], v1 offset:6688
	ds_read_b128 v[124:127], v1 offset:6720
	ds_read_b128 v[128:131], v1 offset:6752
	ds_read_b128 v[132:135], v1 offset:6784
	ds_read_b128 v[136:139], v1 offset:6816
	v_mfma_f32_32x32x16_bf16 v[16:31], v[214:217], v[140:143], v[16:31]
	ds_read2_b64 v[140:143], v14 offset0:0 offset1:2
	v_mfma_f32_32x32x16_bf16 v[32:47], v[214:217], v[144:147], v[32:47]
	ds_read2_b64 v[144:147], v176 offset0:32 offset1:34
	v_mfma_f32_32x32x16_bf16 v[16:31], v[218:221], v[180:183], v[16:31]
	ds_read2_b64 v[180:183], v14 offset0:4 offset1:6
	v_mfma_f32_32x32x16_bf16 v[32:47], v[218:221], v[184:187], v[32:47]
	ds_read2_b64 v[184:187], v176 offset0:36 offset1:38
	v_max3_f32 v15, v64, v65, v66
	v_max3_f32 v177, v67, v68, v69
	v_max3_f32 v15, v15, v70, v71
	v_max3_f32 v177, v177, v72, v73
	v_max3_f32 v15, v15, v74, v75
	v_max3_f32 v177, v177, v76, v77
	v_max3_f32 v15, v15, v78, v79
	v_max_f32_e32 v15, v15, v177
	v_mov_b32_e32 v177, v15
	v_mov_b32_e32 v178, v15
	s_nop 1
	v_permlane32_swap_b32_e32 v177, v178
	v_max3_f32 v15, v15, v177, v178
	v_cmp_gt_f32_e32 vcc, v15, v197
	s_cbranch_vccz .Lm3_ok5
	v_max_f32_e32 v15, v171, v15
	v_sub_f32_e32 v177, v171, v15
	v_exp_f32_e32 v177, v177
	v_sub_f32_e32 v198, v198, v15
	s_and_saveexec_b64 s[20:21], s[40:41]
	ds_write_b32 v149, v177
	s_or_b64 exec, exec, s[20:21]
	v_mul_f32_e32 v170, v170, v177
	v_add_u32_e32 v178, s25, v148
	s_waitcnt lgkmcnt(0)
	ds_read_b128 v[188:191], v178
	ds_read_b128 v[192:195], v178 offset:32
	ds_read_b128 v[222:225], v178 offset:64
	ds_read_b128 v[236:239], v178 offset:96
	v_sub_f32_e32 v64, v64, v15
	v_sub_f32_e32 v65, v65, v15
	v_sub_f32_e32 v66, v66, v15
	v_sub_f32_e32 v67, v67, v15
	v_sub_f32_e32 v68, v68, v15
	v_sub_f32_e32 v69, v69, v15
	v_sub_f32_e32 v70, v70, v15
	v_sub_f32_e32 v71, v71, v15
	v_sub_f32_e32 v72, v72, v15
	v_sub_f32_e32 v73, v73, v15
	v_sub_f32_e32 v74, v74, v15
	v_sub_f32_e32 v75, v75, v15
	v_sub_f32_e32 v76, v76, v15
	v_sub_f32_e32 v77, v77, v15
	v_sub_f32_e32 v78, v78, v15
	v_sub_f32_e32 v79, v79, v15
	v_mov_b32_e32 v199, v198
	v_mov_b32_e32 v200, v198
	v_mov_b32_e32 v201, v198
	v_mov_b32_e32 v202, v198
	v_mov_b32_e32 v203, v198
	v_mov_b32_e32 v204, v198
	v_mov_b32_e32 v205, v198
	v_mov_b32_e32 v206, v198
	v_mov_b32_e32 v207, v198
	v_mov_b32_e32 v208, v198
	v_mov_b32_e32 v209, v198
	v_mov_b32_e32 v210, v198
	v_mov_b32_e32 v211, v198
	v_mov_b32_e32 v212, v198
	v_mov_b32_e32 v213, v198
	v_mov_b32_e32 v171, 0
	v_mov_b32_e32 v197, 0x41000000
	s_nop 11
	s_nop 3
	s_waitcnt lgkmcnt(0)
	v_pk_mul_f32 v[16:17], v[16:17], v[188:189]
	v_pk_mul_f32 v[32:33], v[32:33], v[188:189]
	v_pk_mul_f32 v[18:19], v[18:19], v[190:191]
	v_pk_mul_f32 v[34:35], v[34:35], v[190:191]
	v_pk_mul_f32 v[20:21], v[20:21], v[192:193]
	v_pk_mul_f32 v[36:37], v[36:37], v[192:193]
	v_pk_mul_f32 v[22:23], v[22:23], v[194:195]
	v_pk_mul_f32 v[38:39], v[38:39], v[194:195]
	v_pk_mul_f32 v[24:25], v[24:25], v[222:223]
	v_pk_mul_f32 v[40:41], v[40:41], v[222:223]
	v_pk_mul_f32 v[26:27], v[26:27], v[224:225]
	v_pk_mul_f32 v[42:43], v[42:43], v[224:225]
	v_pk_mul_f32 v[28:29], v[28:29], v[236:237]
	v_pk_mul_f32 v[44:45], v[44:45], v[236:237]
	v_pk_mul_f32 v[30:31], v[30:31], v[238:239]
	v_pk_mul_f32 v[46:47], v[46:47], v[238:239]
